# GEMM peeled first trip (store/load-aware waits + C=0 start) extended to the two w_o GEMMs (8 of 9 GEMM phases)
# speedup vs baseline: 1.0106x; 1.0028x over previous
; #define PG8_STAGE(bufoff, gbase, voff) do { _Pragma("unroll") for (int _i = 0; _i < 2; ++_i) \
;         __builtin_amdgcn_global_load_lds((const unsigned*)((const char*)(gbase) + (voff)[_i]), (PG8_LAS unsigned*)(lds + (bufoff) + ldsw + _i * 8192), 16, 0, 0); } while (0)
; #define PG8_LDA(dst, b, h) do { _Pragma("unroll") for (int m = 0; m < 4; ++m) _Pragma("unroll") for (int k = 0; k < 2; ++k) dst[m][k] = *(const PG8_LAS bf16x8*)(lds + PG8_SA(b, h) + aoff + m * 2048 + k * 1024); } while (0)
; #define PG8_LDB(dst, b, h) do { _Pragma("unroll") for (int n = 0; n < 2; ++n) _Pragma("unroll") for (int k = 0; k < 2; ++k) dst[n][k] = *(const PG8_LAS bf16x8*)(lds + PG8_SB(b, h) + boff + n * 2048 + k * 1024); } while (0)
; #define PG8_SCHED __builtin_amdgcn_sched_barrier(0)
; template <class Epi, class Sched, bool ALIGN_EPI = false, bool SP2 = false>
; __device__ __forceinline__ void gemm_phase(PG8_LAS unsigned char* lds, const Gemm g, const Sched& S, const Epi& E) {
;     ...
;         const bool has_next = S.next(ui + 1, nxt);
;         const char* nA = has_next ? (const char*)g.A + (size_t)nxt.pm * tstep : cA; const char* nB = has_next ? (const char*)g.Bt + (size_t)nxt.pn * tstep : cB;
; #pragma nounroll
;         for (int t = 0; t < nt; t += 2) {
;             const bool last = (t == nt - 2);
;             const char* a1 = cA + (size_t)(t + 1) * kstep;
;             const char* a2 = last ? nA : cA + (size_t)(t + 2) * kstep; const char* b2 = last ? nB : cB + (size_t)(t + 2) * kstep;
;             const char* a3 = a2 + kstep; const char* b3 = b2 + kstep;
;             if (last && has_next) S.a_ready(nxt);
;             if constexpr (SP2) {
;             PG8_LDB(B0, 0, 0); PG8_LDB(B1, 0, 1); PG8_SCHED; PG8_LDA(At, 0, 0); PG8_STAGE(PG8_SA(1, 1), a1 + hstep, voffA);
.LBB0_1313:
	s_ashr_i32 s21, s20, 31
	s_lshl_b64 s[22:23], s[20:21], 19
	s_add_u32 s22, s38, s22
	s_addc_u32 s23, s39, s23
	s_and_b64 s[24:25], s[2:3], exec
	s_cselect_b32 s21, s23, s29
	s_cselect_b32 s60, s22, s28
	s_ashr_i32 s19, s18, 31
	s_lshl_b64 s[24:25], s[18:19], 19
	s_add_u32 s24, s40, s24
	s_addc_u32 s25, s41, s25
	s_and_b64 s[34:35], s[2:3], exec
	s_cselect_b32 s19, s25, s31
	s_cselect_b32 s61, s24, s30
	s_add_u32 s28, s28, 0x40080
	s_addc_u32 s29, s29, 0
	s_add_u32 s62, s30, 0x100
	s_addc_u32 s63, s31, 0
	s_mov_b32 s64, -2
	ds_read_b128 v[146:149], v154
	ds_read_b128 v[158:161], v154 offset:1024
	ds_read_b128 v[162:165], v154 offset:2048
	ds_read_b128 v[166:169], v154 offset:3072
	ds_read_b128 v[174:177], v155
	ds_read_b128 v[178:181], v155 offset:1024
	ds_read_b128 v[182:185], v155 offset:2048
	ds_read_b128 v[186:189], v155 offset:3072
	s_add_u32 s30, s28, 0xfffc0080
	s_addc_u32 s31, s29, -1
	s_cmp_eq_u32 s64, 12
	s_cselect_b32 s35, s21, s31
	s_cselect_b32 s34, s60, s30
	s_cselect_b32 s31, s19, s63
	s_cselect_b32 s30, s61, s62

; #define PG8_STAGE(bufoff, gbase, voff) do { _Pragma("unroll") for (int _i = 0; _i < 2; ++_i) \
;         __builtin_amdgcn_global_load_lds((const unsigned*)((const char*)(gbase) + (voff)[_i]), (PG8_LAS unsigned*)(lds + (bufoff) + ldsw + _i * 8192), 16, 0, 0); } while (0)
; #define PG8_LDA(dst, b, h) do { _Pragma("unroll") for (int m = 0; m < 4; ++m) _Pragma("unroll") for (int k = 0; k < 2; ++k) dst[m][k] = *(const PG8_LAS bf16x8*)(lds + PG8_SA(b, h) + aoff + m * 2048 + k * 1024); } while (0)
; #define PG8_LDB(dst, b, h) do { _Pragma("unroll") for (int n = 0; n < 2; ++n) _Pragma("unroll") for (int k = 0; k < 2; ++k) dst[n][k] = *(const PG8_LAS bf16x8*)(lds + PG8_SB(b, h) + boff + n * 2048 + k * 1024); } while (0)
; #define PG8_MMA(ai, bj, At, Bt) do { __builtin_amdgcn_s_setprio(1); _Pragma("unroll") for (int m = 0; m < 4; ++m) _Pragma("unroll") for (int n = 0; n < 2; ++n) _Pragma("unroll") for (int k = 0; k < 2; ++k) \
;         acc[ai][bj][m][n] = __builtin_amdgcn_mfma_f32_16x16x32_bf16(Bt[n][k], At[m][k], acc[ai][bj][m][n], 0, 0, 0); __builtin_amdgcn_s_setprio(0); } while (0)
; #define PG8_WAIT_V(n) asm volatile("s_waitcnt vmcnt(" #n ")" ::: "memory")
; #define PG8_WAIT_L(n) asm volatile("s_waitcnt lgkmcnt(" #n ")" ::: "memory")
; #define PG8_BAR __builtin_amdgcn_s_barrier()
; #define PG8_SCHED __builtin_amdgcn_sched_barrier(0)
; template <class Epi, class Sched, bool ALIGN_EPI = false, bool SP2 = false>
; __device__ __forceinline__ void gemm_phase(PG8_LAS unsigned char* lds, const Gemm g, const Sched& S, const Epi& E) {
;     ...
;             PG8_LDB(B0, 0, 0); PG8_LDB(B1, 0, 1); PG8_SCHED; PG8_LDA(At, 0, 0); PG8_STAGE(PG8_SA(1, 1), a1 + hstep, voffA);
;             PG8_WAIT_V(8); PG8_WAIT_L(0); PG8_BAR; PG8_MMA(0, 0, At, B0); PG8_MMA(0, 1, At, B1); PG8_BAR; PG8_SCHED;
	v_lshl_add_u64 v[150:151], s[28:29], 0, v[138:139]
	s_add_i32 m0, s27, 0xc000
	ds_read_b128 v[190:193], v156
	ds_read_b128 v[194:197], v156 offset:1024
	ds_read_b128 v[198:201], v156 offset:2048
	ds_read_b128 v[202:205], v156 offset:3072
	ds_read_b128 v[206:209], v156 offset:4096
	ds_read_b128 v[210:213], v156 offset:5120
	ds_read_b128 v[214:217], v156 offset:6144
	ds_read_b128 v[218:221], v156 offset:7168
	global_load_lds_dwordx4 v[150:151], off
	v_lshl_add_u64 v[150:151], s[28:29], 0, v[140:141]
	s_add_i32 m0, s27, 0xe000
	s_nop 0
	global_load_lds_dwordx4 v[150:151], off
	s_waitcnt vmcnt(40)
	s_waitcnt lgkmcnt(0)
	s_barrier
	s_setprio 1
	s_waitcnt lgkmcnt(0)
	v_mfma_f32_16x16x32_bf16 v[126:129], v[146:149], v[190:193], 0
	v_mfma_f32_16x16x32_bf16 v[122:125], v[162:165], v[190:193], 0
	v_mfma_f32_16x16x32_bf16 v[114:117], v[146:149], v[198:201], 0
	v_mfma_f32_16x16x32_bf16 v[106:109], v[162:165], v[198:201], 0
	v_mfma_f32_16x16x32_bf16 v[98:101], v[146:149], v[206:209], 0
	v_mfma_f32_16x16x32_bf16 v[90:93], v[162:165], v[206:209], 0
	v_mfma_f32_16x16x32_bf16 v[82:85], v[146:149], v[214:217], 0
	v_mfma_f32_16x16x32_bf16 v[74:77], v[162:165], v[214:217], 0
	v_mfma_f32_16x16x32_bf16 v[126:129], v[158:161], v[194:197], v[126:129]
	v_mfma_f32_16x16x32_bf16 v[122:125], v[166:169], v[194:197], v[122:125]
	v_mfma_f32_16x16x32_bf16 v[114:117], v[158:161], v[202:205], v[114:117]
	v_mfma_f32_16x16x32_bf16 v[106:109], v[166:169], v[202:205], v[106:109]
	v_mfma_f32_16x16x32_bf16 v[98:101], v[158:161], v[210:213], v[98:101]
	v_mfma_f32_16x16x32_bf16 v[90:93], v[166:169], v[210:213], v[90:93]
	v_mfma_f32_16x16x32_bf16 v[82:85], v[158:161], v[218:221], v[82:85]
	v_mfma_f32_16x16x32_bf16 v[74:77], v[166:169], v[218:221], v[74:77]
	s_setprio 0
	s_setprio 1
	v_mfma_f32_16x16x32_bf16 v[118:121], v[174:177], v[190:193], 0
	v_mfma_f32_16x16x32_bf16 v[110:113], v[182:185], v[190:193], 0
	v_mfma_f32_16x16x32_bf16 v[102:105], v[174:177], v[198:201], 0
	v_mfma_f32_16x16x32_bf16 v[94:97], v[182:185], v[198:201], 0
	v_mfma_f32_16x16x32_bf16 v[86:89], v[174:177], v[206:209], 0
	v_mfma_f32_16x16x32_bf16 v[78:81], v[182:185], v[206:209], 0
	v_mfma_f32_16x16x32_bf16 v[70:73], v[174:177], v[214:217], 0
	v_mfma_f32_16x16x32_bf16 v[66:69], v[182:185], v[214:217], 0
	v_mfma_f32_16x16x32_bf16 v[118:121], v[178:181], v[194:197], v[118:121]
	v_mfma_f32_16x16x32_bf16 v[110:113], v[186:189], v[194:197], v[110:113]
	v_mfma_f32_16x16x32_bf16 v[102:105], v[178:181], v[202:205], v[102:105]
	v_mfma_f32_16x16x32_bf16 v[94:97], v[186:189], v[202:205], v[94:97]
	v_mfma_f32_16x16x32_bf16 v[86:89], v[178:181], v[210:213], v[86:89]
	v_mfma_f32_16x16x32_bf16 v[78:81], v[186:189], v[210:213], v[78:81]
	v_mfma_f32_16x16x32_bf16 v[70:73], v[178:181], v[218:221], v[70:73]
	v_mfma_f32_16x16x32_bf16 v[66:69], v[186:189], v[218:221], v[66:69]
	s_setprio 0
	s_barrier

; #define PG8_STAGE(bufoff, gbase, voff) do { _Pragma("unroll") for (int _i = 0; _i < 2; ++_i) \
;         __builtin_amdgcn_global_load_lds((const unsigned*)((const char*)(gbase) + (voff)[_i]), (PG8_LAS unsigned*)(lds + (bufoff) + ldsw + _i * 8192), 16, 0, 0); } while (0)
; #define PG8_LDA(dst, b, h) do { _Pragma("unroll") for (int m = 0; m < 4; ++m) _Pragma("unroll") for (int k = 0; k < 2; ++k) dst[m][k] = *(const PG8_LAS bf16x8*)(lds + PG8_SA(b, h) + aoff + m * 2048 + k * 1024); } while (0)
; #define PG8_MMA(ai, bj, At, Bt) do { __builtin_amdgcn_s_setprio(1); _Pragma("unroll") for (int m = 0; m < 4; ++m) _Pragma("unroll") for (int n = 0; n < 2; ++n) _Pragma("unroll") for (int k = 0; k < 2; ++k) \
;         acc[ai][bj][m][n] = __builtin_amdgcn_mfma_f32_16x16x32_bf16(Bt[n][k], At[m][k], acc[ai][bj][m][n], 0, 0, 0); __builtin_amdgcn_s_setprio(0); } while (0)
; #define PG8_WAIT_V(n) asm volatile("s_waitcnt vmcnt(" #n ")" ::: "memory")
; #define PG8_WAIT_L(n) asm volatile("s_waitcnt lgkmcnt(" #n ")" ::: "memory")
; #define PG8_BAR __builtin_amdgcn_s_barrier()
; #define PG8_SCHED __builtin_amdgcn_sched_barrier(0)
; template <class Epi, class Sched, bool ALIGN_EPI = false, bool SP2 = false>
; __device__ __forceinline__ void gemm_phase(PG8_LAS unsigned char* lds, const Gemm g, const Sched& S, const Epi& E) {
;     ...
;             PG8_LDA(At, 0, 1); PG8_STAGE(PG8_SB(0, 0), b2, voffB); PG8_STAGE(PG8_SB(0, 1), b2 + hstep, voffB); PG8_STAGE(PG8_SA(0, 0), a2, voffA);
;             PG8_WAIT_V(8); PG8_WAIT_L(0); PG8_BAR; PG8_MMA(1, 0, At, B0); PG8_MMA(1, 1, At, B1); PG8_BAR; PG8_SCHED;
	s_add_i32 s65, s57, s42
	v_lshl_add_u64 v[150:151], s[30:31], 0, v[132:133]
	s_mov_b32 m0, s65
	ds_read_b128 v[190:193], v156 offset:16384
	ds_read_b128 v[194:197], v156 offset:17408
	ds_read_b128 v[198:201], v156 offset:18432
	ds_read_b128 v[202:205], v156 offset:19456
	ds_read_b128 v[206:209], v156 offset:20480
	ds_read_b128 v[210:213], v156 offset:21504
	ds_read_b128 v[214:217], v156 offset:22528
	ds_read_b128 v[218:221], v156 offset:23552
	global_load_lds_dwordx4 v[150:151], off
	s_add_i32 m0, s65, 0x2000
	s_add_u32 s66, s30, 0x40000
	v_lshl_add_u64 v[170:171], s[30:31], 0, v[136:137]
	s_addc_u32 s67, s31, 0
	s_add_i32 s65, s58, s42
	global_load_lds_dwordx4 v[170:171], off
	v_lshl_add_u64 v[222:223], s[66:67], 0, v[132:133]
	s_mov_b32 m0, s65
	v_lshl_add_u64 v[224:225], s[34:35], 0, v[134:135]
	global_load_lds_dwordx4 v[222:223], off
	v_lshl_add_u64 v[222:223], s[66:67], 0, v[136:137]
	s_add_i32 m0, s65, 0x2000
	s_nop 0
	global_load_lds_dwordx4 v[222:223], off
	v_lshl_add_u64 v[222:223], s[34:35], 0, v[130:131]
	s_mov_b32 m0, s27
	s_nop 0
	global_load_lds_dwordx4 v[222:223], off
	s_mov_b32 m0, s43
	s_nop 0
	global_load_lds_dwordx4 v[224:225], off
	s_waitcnt vmcnt(40)
	s_waitcnt lgkmcnt(0)
	s_barrier
	s_setprio 1
	s_waitcnt lgkmcnt(0)
	v_mfma_f32_16x16x32_bf16 v[62:65], v[146:149], v[190:193], 0
	v_mfma_f32_16x16x32_bf16 v[58:61], v[162:165], v[190:193], 0
	v_mfma_f32_16x16x32_bf16 v[50:53], v[146:149], v[198:201], 0
	v_mfma_f32_16x16x32_bf16 v[42:45], v[162:165], v[198:201], 0
	v_mfma_f32_16x16x32_bf16 v[34:37], v[146:149], v[206:209], 0
	v_mfma_f32_16x16x32_bf16 v[26:29], v[162:165], v[206:209], 0
	v_mfma_f32_16x16x32_bf16 v[18:21], v[146:149], v[214:217], 0
	v_mfma_f32_16x16x32_bf16 v[10:13], v[162:165], v[214:217], 0
	v_mfma_f32_16x16x32_bf16 v[62:65], v[158:161], v[194:197], v[62:65]
	v_mfma_f32_16x16x32_bf16 v[58:61], v[166:169], v[194:197], v[58:61]
	v_mfma_f32_16x16x32_bf16 v[50:53], v[158:161], v[202:205], v[50:53]
	v_mfma_f32_16x16x32_bf16 v[42:45], v[166:169], v[202:205], v[42:45]
	v_mfma_f32_16x16x32_bf16 v[34:37], v[158:161], v[210:213], v[34:37]
	v_mfma_f32_16x16x32_bf16 v[26:29], v[166:169], v[210:213], v[26:29]
	v_mfma_f32_16x16x32_bf16 v[18:21], v[158:161], v[218:221], v[18:21]
	v_mfma_f32_16x16x32_bf16 v[10:13], v[166:169], v[218:221], v[10:13]
	s_setprio 0
	s_setprio 1
	v_mfma_f32_16x16x32_bf16 v[54:57], v[174:177], v[190:193], 0
	v_mfma_f32_16x16x32_bf16 v[46:49], v[182:185], v[190:193], 0
	v_mfma_f32_16x16x32_bf16 v[38:41], v[174:177], v[198:201], 0
	v_mfma_f32_16x16x32_bf16 v[30:33], v[182:185], v[198:201], 0
	v_mfma_f32_16x16x32_bf16 v[22:25], v[174:177], v[206:209], 0
	v_mfma_f32_16x16x32_bf16 v[14:17], v[182:185], v[206:209], 0
	v_mfma_f32_16x16x32_bf16 v[6:9], v[174:177], v[214:217], 0
	v_mfma_f32_16x16x32_bf16 v[2:5], v[182:185], v[214:217], 0
	v_mfma_f32_16x16x32_bf16 v[54:57], v[178:181], v[194:197], v[54:57]
	v_mfma_f32_16x16x32_bf16 v[46:49], v[186:189], v[194:197], v[46:49]
	v_mfma_f32_16x16x32_bf16 v[38:41], v[178:181], v[202:205], v[38:41]
	v_mfma_f32_16x16x32_bf16 v[30:33], v[186:189], v[202:205], v[30:33]
	v_mfma_f32_16x16x32_bf16 v[22:25], v[178:181], v[210:213], v[22:25]
	v_mfma_f32_16x16x32_bf16 v[14:17], v[186:189], v[210:213], v[14:17]
	v_mfma_f32_16x16x32_bf16 v[6:9], v[178:181], v[218:221], v[6:9]
	v_mfma_f32_16x16x32_bf16 v[2:5], v[186:189], v[218:221], v[2:5]
	s_setprio 0
	s_barrier

; #define PG8_STAGE(bufoff, gbase, voff) do { _Pragma("unroll") for (int _i = 0; _i < 2; ++_i) \
;         __builtin_amdgcn_global_load_lds((const unsigned*)((const char*)(gbase) + (voff)[_i]), (PG8_LAS unsigned*)(lds + (bufoff) + ldsw + _i * 8192), 16, 0, 0); } while (0)
; #define PG8_LDA(dst, b, h) do { _Pragma("unroll") for (int m = 0; m < 4; ++m) _Pragma("unroll") for (int k = 0; k < 2; ++k) dst[m][k] = *(const PG8_LAS bf16x8*)(lds + PG8_SA(b, h) + aoff + m * 2048 + k * 1024); } while (0)
; #define PG8_LDB(dst, b, h) do { _Pragma("unroll") for (int n = 0; n < 2; ++n) _Pragma("unroll") for (int k = 0; k < 2; ++k) dst[n][k] = *(const PG8_LAS bf16x8*)(lds + PG8_SB(b, h) + boff + n * 2048 + k * 1024); } while (0)
; #define PG8_SCHED __builtin_amdgcn_sched_barrier(0)
; template <class Epi, class Sched, bool ALIGN_EPI = false, bool SP2 = false>
; __device__ __forceinline__ void gemm_phase(PG8_LAS unsigned char* lds, const Gemm g, const Sched& S, const Epi& E) {
;     ...
;             PG8_LDB(B0, 1, 0); PG8_LDB(B1, 1, 1); PG8_SCHED; PG8_LDA(At, 1, 0); PG8_STAGE(PG8_SA(0, 1), a2 + hstep, voffA);
	s_add_i32 s65, 0, 0x18000
	v_add_u32_e32 v157, s65, v152
	s_add_i32 s66, 0, 0x1c000
	ds_read_b128 v[146:149], v157
	ds_read_b128 v[158:161], v157 offset:1024
	ds_read_b128 v[162:165], v157 offset:2048
	ds_read_b128 v[166:169], v157 offset:3072
	v_add_u32_e32 v157, s66, v152
	ds_read_b128 v[174:177], v157
	ds_read_b128 v[178:181], v157 offset:1024
	ds_read_b128 v[182:185], v157 offset:2048
	ds_read_b128 v[186:189], v157 offset:3072

; #define PG8_STAGE(bufoff, gbase, voff) do { _Pragma("unroll") for (int _i = 0; _i < 2; ++_i) \
;         __builtin_amdgcn_global_load_lds((const unsigned*)((const char*)(gbase) + (voff)[_i]), (PG8_LAS unsigned*)(lds + (bufoff) + ldsw + _i * 8192), 16, 0, 0); } while (0)
; #define PG8_LDA(dst, b, h) do { _Pragma("unroll") for (int m = 0; m < 4; ++m) _Pragma("unroll") for (int k = 0; k < 2; ++k) dst[m][k] = *(const PG8_LAS bf16x8*)(lds + PG8_SA(b, h) + aoff + m * 2048 + k * 1024); } while (0)
; #define PG8_LDB(dst, b, h) do { _Pragma("unroll") for (int n = 0; n < 2; ++n) _Pragma("unroll") for (int k = 0; k < 2; ++k) dst[n][k] = *(const PG8_LAS bf16x8*)(lds + PG8_SB(b, h) + boff + n * 2048 + k * 1024); } while (0)
; #define PG8_MMA(ai, bj, At, Bt) do { __builtin_amdgcn_s_setprio(1); _Pragma("unroll") for (int m = 0; m < 4; ++m) _Pragma("unroll") for (int n = 0; n < 2; ++n) _Pragma("unroll") for (int k = 0; k < 2; ++k) \
;         acc[ai][bj][m][n] = __builtin_amdgcn_mfma_f32_16x16x32_bf16(Bt[n][k], At[m][k], acc[ai][bj][m][n], 0, 0, 0); __builtin_amdgcn_s_setprio(0); } while (0)
; #define PG8_WAIT_V(n) asm volatile("s_waitcnt vmcnt(" #n ")" ::: "memory")
; #define PG8_WAIT_L(n) asm volatile("s_waitcnt lgkmcnt(" #n ")" ::: "memory")
; #define PG8_BAR __builtin_amdgcn_s_barrier()
; #define PG8_SCHED __builtin_amdgcn_sched_barrier(0)
; template <class Epi, class Sched, bool ALIGN_EPI = false, bool SP2 = false>
; __device__ __forceinline__ void gemm_phase(PG8_LAS unsigned char* lds, const Gemm g, const Sched& S, const Epi& E) {
;     ...
;             PG8_LDB(B0, 1, 0); PG8_LDB(B1, 1, 1); PG8_SCHED; PG8_LDA(At, 1, 0); PG8_STAGE(PG8_SA(0, 1), a2 + hstep, voffA);
;             PG8_WAIT_V(8); PG8_WAIT_L(0); PG8_BAR; PG8_MMA(0, 0, At, B0); PG8_MMA(0, 1, At, B1); PG8_BAR; PG8_SCHED;
	s_add_u32 s34, s34, 0x40000
	s_addc_u32 s35, s35, 0
	s_mov_b32 m0, s44
	v_lshl_add_u64 v[226:227], s[34:35], 0, v[130:131]
	ds_read_b128 v[190:193], v156 offset:32768
	ds_read_b128 v[194:197], v156 offset:33792
	ds_read_b128 v[198:201], v156 offset:34816
	ds_read_b128 v[202:205], v156 offset:35840
	ds_read_b128 v[206:209], v156 offset:36864
	ds_read_b128 v[210:213], v156 offset:37888
	ds_read_b128 v[214:217], v156 offset:38912
	ds_read_b128 v[218:221], v156 offset:39936
	global_load_lds_dwordx4 v[226:227], off
	v_lshl_add_u64 v[226:227], s[34:35], 0, v[134:135]
	s_mov_b32 m0, s45
	s_nop 0
	global_load_lds_dwordx4 v[226:227], off
	s_waitcnt vmcnt(8)
	s_waitcnt lgkmcnt(0)
	s_barrier
	s_setprio 1
	s_waitcnt lgkmcnt(0)
	v_mfma_f32_16x16x32_bf16 v[126:129], v[146:149], v[190:193], v[126:129]
	v_mfma_f32_16x16x32_bf16 v[122:125], v[162:165], v[190:193], v[122:125]
	v_mfma_f32_16x16x32_bf16 v[114:117], v[146:149], v[198:201], v[114:117]
	v_mfma_f32_16x16x32_bf16 v[106:109], v[162:165], v[198:201], v[106:109]
	v_mfma_f32_16x16x32_bf16 v[98:101], v[146:149], v[206:209], v[98:101]
	v_mfma_f32_16x16x32_bf16 v[90:93], v[162:165], v[206:209], v[90:93]
	v_mfma_f32_16x16x32_bf16 v[82:85], v[146:149], v[214:217], v[82:85]
	v_mfma_f32_16x16x32_bf16 v[74:77], v[162:165], v[214:217], v[74:77]
	v_mfma_f32_16x16x32_bf16 v[126:129], v[158:161], v[194:197], v[126:129]
	v_mfma_f32_16x16x32_bf16 v[122:125], v[166:169], v[194:197], v[122:125]
	v_mfma_f32_16x16x32_bf16 v[114:117], v[158:161], v[202:205], v[114:117]
	v_mfma_f32_16x16x32_bf16 v[106:109], v[166:169], v[202:205], v[106:109]
	v_mfma_f32_16x16x32_bf16 v[98:101], v[158:161], v[210:213], v[98:101]
	v_mfma_f32_16x16x32_bf16 v[90:93], v[166:169], v[210:213], v[90:93]
	v_mfma_f32_16x16x32_bf16 v[82:85], v[158:161], v[218:221], v[82:85]
	v_mfma_f32_16x16x32_bf16 v[74:77], v[166:169], v[218:221], v[74:77]
	s_setprio 0
	s_setprio 1
	v_mfma_f32_16x16x32_bf16 v[118:121], v[174:177], v[190:193], v[118:121]
	v_mfma_f32_16x16x32_bf16 v[110:113], v[182:185], v[190:193], v[110:113]
	v_mfma_f32_16x16x32_bf16 v[102:105], v[174:177], v[198:201], v[102:105]
	v_mfma_f32_16x16x32_bf16 v[94:97], v[182:185], v[198:201], v[94:97]
	v_mfma_f32_16x16x32_bf16 v[86:89], v[174:177], v[206:209], v[86:89]
	v_mfma_f32_16x16x32_bf16 v[78:81], v[182:185], v[206:209], v[78:81]
	v_mfma_f32_16x16x32_bf16 v[70:73], v[174:177], v[214:217], v[70:73]
	v_mfma_f32_16x16x32_bf16 v[66:69], v[182:185], v[214:217], v[66:69]
	v_mfma_f32_16x16x32_bf16 v[118:121], v[178:181], v[194:197], v[118:121]
	v_mfma_f32_16x16x32_bf16 v[110:113], v[186:189], v[194:197], v[110:113]
	v_mfma_f32_16x16x32_bf16 v[102:105], v[178:181], v[202:205], v[102:105]
	v_mfma_f32_16x16x32_bf16 v[94:97], v[186:189], v[202:205], v[94:97]
	v_mfma_f32_16x16x32_bf16 v[86:89], v[178:181], v[210:213], v[86:89]
	v_mfma_f32_16x16x32_bf16 v[78:81], v[186:189], v[210:213], v[78:81]
	v_mfma_f32_16x16x32_bf16 v[70:73], v[178:181], v[218:221], v[70:73]
	v_mfma_f32_16x16x32_bf16 v[66:69], v[186:189], v[218:221], v[66:69]
	s_setprio 0
	s_barrier

; #define PG8_STAGE(bufoff, gbase, voff) do { _Pragma("unroll") for (int _i = 0; _i < 2; ++_i) \
;         __builtin_amdgcn_global_load_lds((const unsigned*)((const char*)(gbase) + (voff)[_i]), (PG8_LAS unsigned*)(lds + (bufoff) + ldsw + _i * 8192), 16, 0, 0); } while (0)
; #define PG8_LDA(dst, b, h) do { _Pragma("unroll") for (int m = 0; m < 4; ++m) _Pragma("unroll") for (int k = 0; k < 2; ++k) dst[m][k] = *(const PG8_LAS bf16x8*)(lds + PG8_SA(b, h) + aoff + m * 2048 + k * 1024); } while (0)
; #define PG8_MMA(ai, bj, At, Bt) do { __builtin_amdgcn_s_setprio(1); _Pragma("unroll") for (int m = 0; m < 4; ++m) _Pragma("unroll") for (int n = 0; n < 2; ++n) _Pragma("unroll") for (int k = 0; k < 2; ++k) \
;         acc[ai][bj][m][n] = __builtin_amdgcn_mfma_f32_16x16x32_bf16(Bt[n][k], At[m][k], acc[ai][bj][m][n], 0, 0, 0); __builtin_amdgcn_s_setprio(0); } while (0)
; #define PG8_WAIT_V(n) asm volatile("s_waitcnt vmcnt(" #n ")" ::: "memory")
; #define PG8_WAIT_L(n) asm volatile("s_waitcnt lgkmcnt(" #n ")" ::: "memory")
; #define PG8_BAR __builtin_amdgcn_s_barrier()
; #define PG8_SCHED __builtin_amdgcn_sched_barrier(0)
; template <class Epi, class Sched, bool ALIGN_EPI = false, bool SP2 = false>
; __device__ __forceinline__ void gemm_phase(PG8_LAS unsigned char* lds, const Gemm g, const Sched& S, const Epi& E) {
;     ...
;             PG8_LDA(At, 1, 1); PG8_STAGE(PG8_SB(1, 0), b3, voffB); PG8_STAGE(PG8_SB(1, 1), b3 + hstep, voffB); PG8_STAGE(PG8_SA(1, 0), a3, voffA);
;             PG8_WAIT_V(8); PG8_WAIT_L(0); PG8_BAR; PG8_MMA(1, 0, At, B0); PG8_MMA(1, 1, At, B1); PG8_BAR; PG8_SCHED;
	s_add_i32 s34, s65, s42
	v_lshl_add_u64 v[150:151], v[150:151], 0, s[8:9]
	s_mov_b32 m0, s34
	ds_read_b128 v[190:193], v156 offset:49152
	ds_read_b128 v[194:197], v156 offset:50176
	ds_read_b128 v[198:201], v156 offset:51200
	ds_read_b128 v[202:205], v156 offset:52224
	ds_read_b128 v[206:209], v156 offset:53248
	ds_read_b128 v[210:213], v156 offset:54272
	ds_read_b128 v[214:217], v156 offset:55296
	ds_read_b128 v[218:221], v156 offset:56320
	global_load_lds_dwordx4 v[150:151], off
	s_add_i32 m0, s34, 0x2000
	s_add_u32 s30, s30, 0x40080
	v_lshl_add_u64 v[150:151], v[170:171], 0, s[8:9]
	s_addc_u32 s31, s31, 0
	s_add_i32 s34, s66, s42
	global_load_lds_dwordx4 v[150:151], off
	v_lshl_add_u64 v[150:151], s[30:31], 0, v[132:133]
	s_mov_b32 m0, s34
	s_nop 0
	global_load_lds_dwordx4 v[150:151], off
	v_lshl_add_u64 v[150:151], s[30:31], 0, v[136:137]
	s_add_i32 m0, s34, 0x2000
	s_nop 0
	global_load_lds_dwordx4 v[150:151], off
	v_lshl_add_u64 v[150:151], v[222:223], 0, s[8:9]
	s_mov_b32 m0, s53
	s_nop 0
	global_load_lds_dwordx4 v[150:151], off
	v_lshl_add_u64 v[150:151], v[224:225], 0, s[8:9]
	s_mov_b32 m0, s54
	s_nop 0
	global_load_lds_dwordx4 v[150:151], off
	s_waitcnt vmcnt(8)
	s_waitcnt lgkmcnt(0)
	s_barrier
	s_setprio 1
	s_waitcnt lgkmcnt(0)
	v_mfma_f32_16x16x32_bf16 v[62:65], v[146:149], v[190:193], v[62:65]
	v_mfma_f32_16x16x32_bf16 v[58:61], v[162:165], v[190:193], v[58:61]
	v_mfma_f32_16x16x32_bf16 v[50:53], v[146:149], v[198:201], v[50:53]
	v_mfma_f32_16x16x32_bf16 v[42:45], v[162:165], v[198:201], v[42:45]
	v_mfma_f32_16x16x32_bf16 v[34:37], v[146:149], v[206:209], v[34:37]
	v_mfma_f32_16x16x32_bf16 v[26:29], v[162:165], v[206:209], v[26:29]
	v_mfma_f32_16x16x32_bf16 v[18:21], v[146:149], v[214:217], v[18:21]
	v_mfma_f32_16x16x32_bf16 v[10:13], v[162:165], v[214:217], v[10:13]
	v_mfma_f32_16x16x32_bf16 v[62:65], v[158:161], v[194:197], v[62:65]
	v_mfma_f32_16x16x32_bf16 v[58:61], v[166:169], v[194:197], v[58:61]
	v_mfma_f32_16x16x32_bf16 v[50:53], v[158:161], v[202:205], v[50:53]
	v_mfma_f32_16x16x32_bf16 v[42:45], v[166:169], v[202:205], v[42:45]
	v_mfma_f32_16x16x32_bf16 v[34:37], v[158:161], v[210:213], v[34:37]
	v_mfma_f32_16x16x32_bf16 v[26:29], v[166:169], v[210:213], v[26:29]
	v_mfma_f32_16x16x32_bf16 v[18:21], v[158:161], v[218:221], v[18:21]
	v_mfma_f32_16x16x32_bf16 v[10:13], v[166:169], v[218:221], v[10:13]
	s_setprio 0
	s_setprio 1
	v_mfma_f32_16x16x32_bf16 v[54:57], v[174:177], v[190:193], v[54:57]
	v_mfma_f32_16x16x32_bf16 v[46:49], v[182:185], v[190:193], v[46:49]
	v_mfma_f32_16x16x32_bf16 v[38:41], v[174:177], v[198:201], v[38:41]
	v_mfma_f32_16x16x32_bf16 v[30:33], v[182:185], v[198:201], v[30:33]
	v_mfma_f32_16x16x32_bf16 v[22:25], v[174:177], v[206:209], v[22:25]
	v_mfma_f32_16x16x32_bf16 v[14:17], v[182:185], v[206:209], v[14:17]
	v_mfma_f32_16x16x32_bf16 v[6:9], v[174:177], v[214:217], v[6:9]
	v_mfma_f32_16x16x32_bf16 v[2:5], v[182:185], v[214:217], v[2:5]
	v_mfma_f32_16x16x32_bf16 v[54:57], v[178:181], v[194:197], v[54:57]
	v_mfma_f32_16x16x32_bf16 v[46:49], v[186:189], v[194:197], v[46:49]
	v_mfma_f32_16x16x32_bf16 v[38:41], v[178:181], v[202:205], v[38:41]
	v_mfma_f32_16x16x32_bf16 v[30:33], v[186:189], v[202:205], v[30:33]
	v_mfma_f32_16x16x32_bf16 v[22:25], v[178:181], v[210:213], v[22:25]
	v_mfma_f32_16x16x32_bf16 v[14:17], v[186:189], v[210:213], v[14:17]
	v_mfma_f32_16x16x32_bf16 v[6:9], v[178:181], v[218:221], v[6:9]
	v_mfma_f32_16x16x32_bf16 v[2:5], v[186:189], v[218:221], v[2:5]
	s_setprio 0
	s_barrier

; template <class Epi, class Sched, bool ALIGN_EPI = false, bool SP2 = false>
; __device__ __forceinline__ void gemm_phase(PG8_LAS unsigned char* lds, const Gemm g, const Sched& S, const Epi& E) {
;     ...
;         for (int t = 0; t < nt; t += 2) {
;             const bool last = (t == nt - 2);
;             const char* a1 = cA + (size_t)(t + 1) * kstep;
;             const char* a2 = last ? nA : cA + (size_t)(t + 2) * kstep; const char* b2 = last ? nB : cB + (size_t)(t + 2) * kstep;
;             const char* a3 = a2 + kstep; const char* b3 = b2 + kstep;
	s_add_i32 s64, s64, 2
	s_add_u32 s28, s28, 0x100
	s_addc_u32 s29, s29, 0
	s_add_u32 s62, s62, 0x100
	s_addc_u32 s63, s63, 0

; #define PG8_STAGE(bufoff, gbase, voff) do { _Pragma("unroll") for (int _i = 0; _i < 2; ++_i) \
;         __builtin_amdgcn_global_load_lds((const unsigned*)((const char*)(gbase) + (voff)[_i]), (PG8_LAS unsigned*)(lds + (bufoff) + ldsw + _i * 8192), 16, 0, 0); } while (0)
; #define PG8_LDA(dst, b, h) do { _Pragma("unroll") for (int m = 0; m < 4; ++m) _Pragma("unroll") for (int k = 0; k < 2; ++k) dst[m][k] = *(const PG8_LAS bf16x8*)(lds + PG8_SA(b, h) + aoff + m * 2048 + k * 1024); } while (0)
; #define PG8_LDB(dst, b, h) do { _Pragma("unroll") for (int n = 0; n < 2; ++n) _Pragma("unroll") for (int k = 0; k < 2; ++k) dst[n][k] = *(const PG8_LAS bf16x8*)(lds + PG8_SB(b, h) + boff + n * 2048 + k * 1024); } while (0)
; #define PG8_SCHED __builtin_amdgcn_sched_barrier(0)
; template <class Epi, class Sched, bool ALIGN_EPI = false, bool SP2 = false>
; __device__ __forceinline__ void gemm_phase(PG8_LAS unsigned char* lds, const Gemm g, const Sched& S, const Epi& E) {
;     ...
;         const bool has_next = S.next(ui + 1, nxt);
;         const char* nA = has_next ? (const char*)g.A + (size_t)nxt.pm * tstep : cA; const char* nB = has_next ? (const char*)g.Bt + (size_t)nxt.pn * tstep : cB;
; #pragma nounroll
;         for (int t = 0; t < nt; t += 2) {
;             const bool last = (t == nt - 2);
;             const char* a1 = cA + (size_t)(t + 1) * kstep;
;             const char* a2 = last ? nA : cA + (size_t)(t + 2) * kstep; const char* b2 = last ? nB : cB + (size_t)(t + 2) * kstep;
;             const char* a3 = a2 + kstep; const char* b3 = b2 + kstep;
;             if (last && has_next) S.a_ready(nxt);
;             if constexpr (SP2) {
;             PG8_LDB(B0, 0, 0); PG8_LDB(B1, 0, 1); PG8_SCHED; PG8_LDA(At, 0, 0); PG8_STAGE(PG8_SA(1, 1), a1 + hstep, voffA);
.LBB0_1338:
	s_ashr_i32 s25, s24, 31
	s_lshl_b64 s[26:27], s[24:25], 18
	s_add_u32 s26, s42, s26
	s_addc_u32 s27, s43, s27
	s_and_b64 s[28:29], s[2:3], exec
	s_cselect_b32 s25, s27, s35
	s_cselect_b32 s64, s26, s34
	s_ashr_i32 s23, s22, 31
	s_lshl_b64 s[28:29], s[22:23], 18
	s_add_u32 s28, s44, s28
	s_addc_u32 s29, s45, s29
	s_and_b64 s[40:41], s[2:3], exec
	s_cselect_b32 s23, s29, s39
	s_cselect_b32 s65, s28, s38
	s_add_u32 s34, s34, 0x20080
	s_addc_u32 s35, s35, 0
	s_add_u32 s66, s38, 0x100
	s_addc_u32 s67, s39, 0
	s_mov_b32 s68, -2
	ds_read_b128 v[146:149], v154
	ds_read_b128 v[158:161], v154 offset:1024
	ds_read_b128 v[162:165], v154 offset:2048
	ds_read_b128 v[166:169], v154 offset:3072
	ds_read_b128 v[174:177], v155
	ds_read_b128 v[178:181], v155 offset:1024
	ds_read_b128 v[182:185], v155 offset:2048
	ds_read_b128 v[186:189], v155 offset:3072
	s_add_u32 s38, s34, 0xfffe0080
	s_addc_u32 s39, s35, -1
	s_cmp_eq_u32 s68, 4
	s_cselect_b32 s41, s25, s39
	s_cselect_b32 s40, s64, s38
	s_cselect_b32 s39, s23, s67
	s_cselect_b32 s38, s65, s66

; #define PG8_STAGE(bufoff, gbase, voff) do { _Pragma("unroll") for (int _i = 0; _i < 2; ++_i) \
;         __builtin_amdgcn_global_load_lds((const unsigned*)((const char*)(gbase) + (voff)[_i]), (PG8_LAS unsigned*)(lds + (bufoff) + ldsw + _i * 8192), 16, 0, 0); } while (0)
; #define PG8_LDA(dst, b, h) do { _Pragma("unroll") for (int m = 0; m < 4; ++m) _Pragma("unroll") for (int k = 0; k < 2; ++k) dst[m][k] = *(const PG8_LAS bf16x8*)(lds + PG8_SA(b, h) + aoff + m * 2048 + k * 1024); } while (0)
; #define PG8_LDB(dst, b, h) do { _Pragma("unroll") for (int n = 0; n < 2; ++n) _Pragma("unroll") for (int k = 0; k < 2; ++k) dst[n][k] = *(const PG8_LAS bf16x8*)(lds + PG8_SB(b, h) + boff + n * 2048 + k * 1024); } while (0)
; #define PG8_MMA(ai, bj, At, Bt) do { __builtin_amdgcn_s_setprio(1); _Pragma("unroll") for (int m = 0; m < 4; ++m) _Pragma("unroll") for (int n = 0; n < 2; ++n) _Pragma("unroll") for (int k = 0; k < 2; ++k) \
;         acc[ai][bj][m][n] = __builtin_amdgcn_mfma_f32_16x16x32_bf16(Bt[n][k], At[m][k], acc[ai][bj][m][n], 0, 0, 0); __builtin_amdgcn_s_setprio(0); } while (0)
; #define PG8_WAIT_V(n) asm volatile("s_waitcnt vmcnt(" #n ")" ::: "memory")
; #define PG8_WAIT_L(n) asm volatile("s_waitcnt lgkmcnt(" #n ")" ::: "memory")
; #define PG8_BAR __builtin_amdgcn_s_barrier()
; #define PG8_SCHED __builtin_amdgcn_sched_barrier(0)
; template <class Epi, class Sched, bool ALIGN_EPI = false, bool SP2 = false>
; __device__ __forceinline__ void gemm_phase(PG8_LAS unsigned char* lds, const Gemm g, const Sched& S, const Epi& E) {
;     ...
;             PG8_LDB(B0, 0, 0); PG8_LDB(B1, 0, 1); PG8_SCHED; PG8_LDA(At, 0, 0); PG8_STAGE(PG8_SA(1, 1), a1 + hstep, voffA);
;             PG8_WAIT_V(8); PG8_WAIT_L(0); PG8_BAR; PG8_MMA(0, 0, At, B0); PG8_MMA(0, 1, At, B1); PG8_BAR; PG8_SCHED;
	v_lshl_add_u64 v[150:151], s[34:35], 0, v[138:139]
	s_add_i32 m0, s31, 0xc000
	ds_read_b128 v[190:193], v156
	ds_read_b128 v[194:197], v156 offset:1024
	ds_read_b128 v[198:201], v156 offset:2048
	ds_read_b128 v[202:205], v156 offset:3072
	ds_read_b128 v[206:209], v156 offset:4096
	ds_read_b128 v[210:213], v156 offset:5120
	ds_read_b128 v[214:217], v156 offset:6144
	ds_read_b128 v[218:221], v156 offset:7168
	global_load_lds_dwordx4 v[150:151], off
	v_lshl_add_u64 v[150:151], s[34:35], 0, v[140:141]
	s_add_i32 m0, s31, 0xe000
	s_nop 0
	global_load_lds_dwordx4 v[150:151], off
	s_waitcnt vmcnt(56)
	s_waitcnt lgkmcnt(0)
	s_barrier
	s_setprio 1
	s_waitcnt lgkmcnt(0)
	v_mfma_f32_16x16x32_bf16 v[126:129], v[146:149], v[190:193], 0
	v_mfma_f32_16x16x32_bf16 v[122:125], v[162:165], v[190:193], 0
	v_mfma_f32_16x16x32_bf16 v[110:113], v[146:149], v[198:201], 0
	v_mfma_f32_16x16x32_bf16 v[106:109], v[162:165], v[198:201], 0
	v_mfma_f32_16x16x32_bf16 v[94:97], v[146:149], v[206:209], 0
	v_mfma_f32_16x16x32_bf16 v[90:93], v[162:165], v[206:209], 0
	v_mfma_f32_16x16x32_bf16 v[78:81], v[146:149], v[214:217], 0
	v_mfma_f32_16x16x32_bf16 v[74:77], v[162:165], v[214:217], 0
	v_mfma_f32_16x16x32_bf16 v[126:129], v[158:161], v[194:197], v[126:129]
	v_mfma_f32_16x16x32_bf16 v[122:125], v[166:169], v[194:197], v[122:125]
	v_mfma_f32_16x16x32_bf16 v[110:113], v[158:161], v[202:205], v[110:113]
	v_mfma_f32_16x16x32_bf16 v[106:109], v[166:169], v[202:205], v[106:109]
	v_mfma_f32_16x16x32_bf16 v[94:97], v[158:161], v[210:213], v[94:97]
	v_mfma_f32_16x16x32_bf16 v[90:93], v[166:169], v[210:213], v[90:93]
	v_mfma_f32_16x16x32_bf16 v[78:81], v[158:161], v[218:221], v[78:81]
	v_mfma_f32_16x16x32_bf16 v[74:77], v[166:169], v[218:221], v[74:77]
	s_setprio 0
	s_setprio 1
	v_mfma_f32_16x16x32_bf16 v[118:121], v[174:177], v[190:193], 0
	v_mfma_f32_16x16x32_bf16 v[114:117], v[182:185], v[190:193], 0
	v_mfma_f32_16x16x32_bf16 v[102:105], v[174:177], v[198:201], 0
	v_mfma_f32_16x16x32_bf16 v[98:101], v[182:185], v[198:201], 0
	v_mfma_f32_16x16x32_bf16 v[86:89], v[174:177], v[206:209], 0
	v_mfma_f32_16x16x32_bf16 v[82:85], v[182:185], v[206:209], 0
	v_mfma_f32_16x16x32_bf16 v[70:73], v[174:177], v[214:217], 0
	v_mfma_f32_16x16x32_bf16 v[66:69], v[182:185], v[214:217], 0
	v_mfma_f32_16x16x32_bf16 v[118:121], v[178:181], v[194:197], v[118:121]
	v_mfma_f32_16x16x32_bf16 v[114:117], v[186:189], v[194:197], v[114:117]
	v_mfma_f32_16x16x32_bf16 v[102:105], v[178:181], v[202:205], v[102:105]
	v_mfma_f32_16x16x32_bf16 v[98:101], v[186:189], v[202:205], v[98:101]
	v_mfma_f32_16x16x32_bf16 v[86:89], v[178:181], v[210:213], v[86:89]
	v_mfma_f32_16x16x32_bf16 v[82:85], v[186:189], v[210:213], v[82:85]
	v_mfma_f32_16x16x32_bf16 v[70:73], v[178:181], v[218:221], v[70:73]
	v_mfma_f32_16x16x32_bf16 v[66:69], v[186:189], v[218:221], v[66:69]
	s_setprio 0
	s_barrier

; #define PG8_STAGE(bufoff, gbase, voff) do { _Pragma("unroll") for (int _i = 0; _i < 2; ++_i) \
;         __builtin_amdgcn_global_load_lds((const unsigned*)((const char*)(gbase) + (voff)[_i]), (PG8_LAS unsigned*)(lds + (bufoff) + ldsw + _i * 8192), 16, 0, 0); } while (0)
; #define PG8_LDA(dst, b, h) do { _Pragma("unroll") for (int m = 0; m < 4; ++m) _Pragma("unroll") for (int k = 0; k < 2; ++k) dst[m][k] = *(const PG8_LAS bf16x8*)(lds + PG8_SA(b, h) + aoff + m * 2048 + k * 1024); } while (0)
; #define PG8_MMA(ai, bj, At, Bt) do { __builtin_amdgcn_s_setprio(1); _Pragma("unroll") for (int m = 0; m < 4; ++m) _Pragma("unroll") for (int n = 0; n < 2; ++n) _Pragma("unroll") for (int k = 0; k < 2; ++k) \
;         acc[ai][bj][m][n] = __builtin_amdgcn_mfma_f32_16x16x32_bf16(Bt[n][k], At[m][k], acc[ai][bj][m][n], 0, 0, 0); __builtin_amdgcn_s_setprio(0); } while (0)
; #define PG8_WAIT_V(n) asm volatile("s_waitcnt vmcnt(" #n ")" ::: "memory")
; #define PG8_WAIT_L(n) asm volatile("s_waitcnt lgkmcnt(" #n ")" ::: "memory")
; #define PG8_BAR __builtin_amdgcn_s_barrier()
; #define PG8_SCHED __builtin_amdgcn_sched_barrier(0)
; template <class Epi, class Sched, bool ALIGN_EPI = false, bool SP2 = false>
; __device__ __forceinline__ void gemm_phase(PG8_LAS unsigned char* lds, const Gemm g, const Sched& S, const Epi& E) {
;     ...
;             PG8_LDA(At, 0, 1); PG8_STAGE(PG8_SB(0, 0), b2, voffB); PG8_STAGE(PG8_SB(0, 1), b2 + hstep, voffB); PG8_STAGE(PG8_SA(0, 0), a2, voffA);
;             PG8_WAIT_V(8); PG8_WAIT_L(0); PG8_BAR; PG8_MMA(1, 0, At, B0); PG8_MMA(1, 1, At, B1); PG8_BAR; PG8_SCHED;
	s_add_i32 s69, s61, s52
	v_lshl_add_u64 v[150:151], s[38:39], 0, v[132:133]
	s_mov_b32 m0, s69
	ds_read_b128 v[190:193], v156 offset:16384
	ds_read_b128 v[194:197], v156 offset:17408
	ds_read_b128 v[198:201], v156 offset:18432
	ds_read_b128 v[202:205], v156 offset:19456
	ds_read_b128 v[206:209], v156 offset:20480
	ds_read_b128 v[210:213], v156 offset:21504
	ds_read_b128 v[214:217], v156 offset:22528
	ds_read_b128 v[218:221], v156 offset:23552
	global_load_lds_dwordx4 v[150:151], off
	s_add_i32 m0, s69, 0x2000
	s_add_u32 s70, s38, 0x20000
	v_lshl_add_u64 v[170:171], s[38:39], 0, v[136:137]
	s_addc_u32 s71, s39, 0
	s_add_i32 s69, s62, s52
	global_load_lds_dwordx4 v[170:171], off
	v_lshl_add_u64 v[222:223], s[70:71], 0, v[132:133]
	s_mov_b32 m0, s69
	v_lshl_add_u64 v[224:225], s[40:41], 0, v[134:135]
	global_load_lds_dwordx4 v[222:223], off
	v_lshl_add_u64 v[222:223], s[70:71], 0, v[136:137]
	s_add_i32 m0, s69, 0x2000
	s_nop 0
	global_load_lds_dwordx4 v[222:223], off
	v_lshl_add_u64 v[222:223], s[40:41], 0, v[130:131]
	s_mov_b32 m0, s31
	s_nop 0
	global_load_lds_dwordx4 v[222:223], off
	s_mov_b32 m0, s53
	s_nop 0
	global_load_lds_dwordx4 v[224:225], off
	s_waitcnt vmcnt(56)
	s_waitcnt lgkmcnt(0)
	s_barrier
	s_setprio 1
	s_waitcnt lgkmcnt(0)
	v_mfma_f32_16x16x32_bf16 v[62:65], v[146:149], v[190:193], 0
	v_mfma_f32_16x16x32_bf16 v[58:61], v[162:165], v[190:193], 0
	v_mfma_f32_16x16x32_bf16 v[46:49], v[146:149], v[198:201], 0
	v_mfma_f32_16x16x32_bf16 v[42:45], v[162:165], v[198:201], 0
	v_mfma_f32_16x16x32_bf16 v[30:33], v[146:149], v[206:209], 0
	v_mfma_f32_16x16x32_bf16 v[26:29], v[162:165], v[206:209], 0
	v_mfma_f32_16x16x32_bf16 v[14:17], v[146:149], v[214:217], 0
	v_mfma_f32_16x16x32_bf16 v[10:13], v[162:165], v[214:217], 0
	v_mfma_f32_16x16x32_bf16 v[62:65], v[158:161], v[194:197], v[62:65]
	v_mfma_f32_16x16x32_bf16 v[58:61], v[166:169], v[194:197], v[58:61]
	v_mfma_f32_16x16x32_bf16 v[46:49], v[158:161], v[202:205], v[46:49]
	v_mfma_f32_16x16x32_bf16 v[42:45], v[166:169], v[202:205], v[42:45]
	v_mfma_f32_16x16x32_bf16 v[30:33], v[158:161], v[210:213], v[30:33]
	v_mfma_f32_16x16x32_bf16 v[26:29], v[166:169], v[210:213], v[26:29]
	v_mfma_f32_16x16x32_bf16 v[14:17], v[158:161], v[218:221], v[14:17]
	v_mfma_f32_16x16x32_bf16 v[10:13], v[166:169], v[218:221], v[10:13]
	s_setprio 0
	s_setprio 1
	v_mfma_f32_16x16x32_bf16 v[54:57], v[174:177], v[190:193], 0
	v_mfma_f32_16x16x32_bf16 v[50:53], v[182:185], v[190:193], 0
	v_mfma_f32_16x16x32_bf16 v[38:41], v[174:177], v[198:201], 0
	v_mfma_f32_16x16x32_bf16 v[34:37], v[182:185], v[198:201], 0
	v_mfma_f32_16x16x32_bf16 v[22:25], v[174:177], v[206:209], 0
	v_mfma_f32_16x16x32_bf16 v[18:21], v[182:185], v[206:209], 0
	v_mfma_f32_16x16x32_bf16 v[6:9], v[174:177], v[214:217], 0
	v_mfma_f32_16x16x32_bf16 v[2:5], v[182:185], v[214:217], 0
	v_mfma_f32_16x16x32_bf16 v[54:57], v[178:181], v[194:197], v[54:57]
	v_mfma_f32_16x16x32_bf16 v[50:53], v[186:189], v[194:197], v[50:53]
	v_mfma_f32_16x16x32_bf16 v[38:41], v[178:181], v[202:205], v[38:41]
	v_mfma_f32_16x16x32_bf16 v[34:37], v[186:189], v[202:205], v[34:37]
	v_mfma_f32_16x16x32_bf16 v[22:25], v[178:181], v[210:213], v[22:25]
	v_mfma_f32_16x16x32_bf16 v[18:21], v[186:189], v[210:213], v[18:21]
	v_mfma_f32_16x16x32_bf16 v[6:9], v[178:181], v[218:221], v[6:9]
	v_mfma_f32_16x16x32_bf16 v[2:5], v[186:189], v[218:221], v[2:5]
	s_setprio 0
	s_barrier

; #define PG8_STAGE(bufoff, gbase, voff) do { _Pragma("unroll") for (int _i = 0; _i < 2; ++_i) \
;         __builtin_amdgcn_global_load_lds((const unsigned*)((const char*)(gbase) + (voff)[_i]), (PG8_LAS unsigned*)(lds + (bufoff) + ldsw + _i * 8192), 16, 0, 0); } while (0)
; #define PG8_LDA(dst, b, h) do { _Pragma("unroll") for (int m = 0; m < 4; ++m) _Pragma("unroll") for (int k = 0; k < 2; ++k) dst[m][k] = *(const PG8_LAS bf16x8*)(lds + PG8_SA(b, h) + aoff + m * 2048 + k * 1024); } while (0)
; #define PG8_LDB(dst, b, h) do { _Pragma("unroll") for (int n = 0; n < 2; ++n) _Pragma("unroll") for (int k = 0; k < 2; ++k) dst[n][k] = *(const PG8_LAS bf16x8*)(lds + PG8_SB(b, h) + boff + n * 2048 + k * 1024); } while (0)
; #define PG8_SCHED __builtin_amdgcn_sched_barrier(0)
; template <class Epi, class Sched, bool ALIGN_EPI = false, bool SP2 = false>
; __device__ __forceinline__ void gemm_phase(PG8_LAS unsigned char* lds, const Gemm g, const Sched& S, const Epi& E) {
;     ...
;             PG8_LDB(B0, 1, 0); PG8_LDB(B1, 1, 1); PG8_SCHED; PG8_LDA(At, 1, 0); PG8_STAGE(PG8_SA(0, 1), a2 + hstep, voffA);
	s_add_i32 s69, 0, 0x18000
	v_add_u32_e32 v157, s69, v152
	s_add_i32 s70, 0, 0x1c000
	ds_read_b128 v[146:149], v157
	ds_read_b128 v[158:161], v157 offset:1024
	ds_read_b128 v[162:165], v157 offset:2048
	ds_read_b128 v[166:169], v157 offset:3072
	v_add_u32_e32 v157, s70, v152
	ds_read_b128 v[174:177], v157
	ds_read_b128 v[178:181], v157 offset:1024
	ds_read_b128 v[182:185], v157 offset:2048
	ds_read_b128 v[186:189], v157 offset:3072

; #define PG8_STAGE(bufoff, gbase, voff) do { _Pragma("unroll") for (int _i = 0; _i < 2; ++_i) \
;         __builtin_amdgcn_global_load_lds((const unsigned*)((const char*)(gbase) + (voff)[_i]), (PG8_LAS unsigned*)(lds + (bufoff) + ldsw + _i * 8192), 16, 0, 0); } while (0)
; #define PG8_LDA(dst, b, h) do { _Pragma("unroll") for (int m = 0; m < 4; ++m) _Pragma("unroll") for (int k = 0; k < 2; ++k) dst[m][k] = *(const PG8_LAS bf16x8*)(lds + PG8_SA(b, h) + aoff + m * 2048 + k * 1024); } while (0)
; #define PG8_LDB(dst, b, h) do { _Pragma("unroll") for (int n = 0; n < 2; ++n) _Pragma("unroll") for (int k = 0; k < 2; ++k) dst[n][k] = *(const PG8_LAS bf16x8*)(lds + PG8_SB(b, h) + boff + n * 2048 + k * 1024); } while (0)
; #define PG8_MMA(ai, bj, At, Bt) do { __builtin_amdgcn_s_setprio(1); _Pragma("unroll") for (int m = 0; m < 4; ++m) _Pragma("unroll") for (int n = 0; n < 2; ++n) _Pragma("unroll") for (int k = 0; k < 2; ++k) \
;         acc[ai][bj][m][n] = __builtin_amdgcn_mfma_f32_16x16x32_bf16(Bt[n][k], At[m][k], acc[ai][bj][m][n], 0, 0, 0); __builtin_amdgcn_s_setprio(0); } while (0)
; #define PG8_WAIT_V(n) asm volatile("s_waitcnt vmcnt(" #n ")" ::: "memory")
; #define PG8_WAIT_L(n) asm volatile("s_waitcnt lgkmcnt(" #n ")" ::: "memory")
; #define PG8_BAR __builtin_amdgcn_s_barrier()
; #define PG8_SCHED __builtin_amdgcn_sched_barrier(0)
; template <class Epi, class Sched, bool ALIGN_EPI = false, bool SP2 = false>
; __device__ __forceinline__ void gemm_phase(PG8_LAS unsigned char* lds, const Gemm g, const Sched& S, const Epi& E) {
;     ...
;             PG8_LDB(B0, 1, 0); PG8_LDB(B1, 1, 1); PG8_SCHED; PG8_LDA(At, 1, 0); PG8_STAGE(PG8_SA(0, 1), a2 + hstep, voffA);
;             PG8_WAIT_V(8); PG8_WAIT_L(0); PG8_BAR; PG8_MMA(0, 0, At, B0); PG8_MMA(0, 1, At, B1); PG8_BAR; PG8_SCHED;
	s_add_u32 s40, s40, 0x20000
	s_addc_u32 s41, s41, 0
	s_mov_b32 m0, s54
	v_lshl_add_u64 v[226:227], s[40:41], 0, v[130:131]
	ds_read_b128 v[190:193], v156 offset:32768
	ds_read_b128 v[194:197], v156 offset:33792
	ds_read_b128 v[198:201], v156 offset:34816
	ds_read_b128 v[202:205], v156 offset:35840
	ds_read_b128 v[206:209], v156 offset:36864
	ds_read_b128 v[210:213], v156 offset:37888
	ds_read_b128 v[214:217], v156 offset:38912
	ds_read_b128 v[218:221], v156 offset:39936
	global_load_lds_dwordx4 v[226:227], off
	v_lshl_add_u64 v[226:227], s[40:41], 0, v[134:135]
	s_mov_b32 m0, s55
	s_nop 0
	global_load_lds_dwordx4 v[226:227], off
	s_waitcnt vmcnt(8)
	s_waitcnt lgkmcnt(0)
	s_barrier
	s_setprio 1
	s_waitcnt lgkmcnt(0)
	v_mfma_f32_16x16x32_bf16 v[126:129], v[146:149], v[190:193], v[126:129]
	v_mfma_f32_16x16x32_bf16 v[122:125], v[162:165], v[190:193], v[122:125]
	v_mfma_f32_16x16x32_bf16 v[110:113], v[146:149], v[198:201], v[110:113]
	v_mfma_f32_16x16x32_bf16 v[106:109], v[162:165], v[198:201], v[106:109]
	v_mfma_f32_16x16x32_bf16 v[94:97], v[146:149], v[206:209], v[94:97]
	v_mfma_f32_16x16x32_bf16 v[90:93], v[162:165], v[206:209], v[90:93]
	v_mfma_f32_16x16x32_bf16 v[78:81], v[146:149], v[214:217], v[78:81]
	v_mfma_f32_16x16x32_bf16 v[74:77], v[162:165], v[214:217], v[74:77]
	v_mfma_f32_16x16x32_bf16 v[126:129], v[158:161], v[194:197], v[126:129]
	v_mfma_f32_16x16x32_bf16 v[122:125], v[166:169], v[194:197], v[122:125]
	v_mfma_f32_16x16x32_bf16 v[110:113], v[158:161], v[202:205], v[110:113]
	v_mfma_f32_16x16x32_bf16 v[106:109], v[166:169], v[202:205], v[106:109]
	v_mfma_f32_16x16x32_bf16 v[94:97], v[158:161], v[210:213], v[94:97]
	v_mfma_f32_16x16x32_bf16 v[90:93], v[166:169], v[210:213], v[90:93]
	v_mfma_f32_16x16x32_bf16 v[78:81], v[158:161], v[218:221], v[78:81]
	v_mfma_f32_16x16x32_bf16 v[74:77], v[166:169], v[218:221], v[74:77]
	s_setprio 0
	s_setprio 1
	v_mfma_f32_16x16x32_bf16 v[118:121], v[174:177], v[190:193], v[118:121]
	v_mfma_f32_16x16x32_bf16 v[114:117], v[182:185], v[190:193], v[114:117]
	v_mfma_f32_16x16x32_bf16 v[102:105], v[174:177], v[198:201], v[102:105]
	v_mfma_f32_16x16x32_bf16 v[98:101], v[182:185], v[198:201], v[98:101]
	v_mfma_f32_16x16x32_bf16 v[86:89], v[174:177], v[206:209], v[86:89]
	v_mfma_f32_16x16x32_bf16 v[82:85], v[182:185], v[206:209], v[82:85]
	v_mfma_f32_16x16x32_bf16 v[70:73], v[174:177], v[214:217], v[70:73]
	v_mfma_f32_16x16x32_bf16 v[66:69], v[182:185], v[214:217], v[66:69]
	v_mfma_f32_16x16x32_bf16 v[118:121], v[178:181], v[194:197], v[118:121]
	v_mfma_f32_16x16x32_bf16 v[114:117], v[186:189], v[194:197], v[114:117]
	v_mfma_f32_16x16x32_bf16 v[102:105], v[178:181], v[202:205], v[102:105]
	v_mfma_f32_16x16x32_bf16 v[98:101], v[186:189], v[202:205], v[98:101]
	v_mfma_f32_16x16x32_bf16 v[86:89], v[178:181], v[210:213], v[86:89]
	v_mfma_f32_16x16x32_bf16 v[82:85], v[186:189], v[210:213], v[82:85]
	v_mfma_f32_16x16x32_bf16 v[70:73], v[178:181], v[218:221], v[70:73]
	v_mfma_f32_16x16x32_bf16 v[66:69], v[186:189], v[218:221], v[66:69]
	s_setprio 0
	s_barrier

; #define PG8_STAGE(bufoff, gbase, voff) do { _Pragma("unroll") for (int _i = 0; _i < 2; ++_i) \
;         __builtin_amdgcn_global_load_lds((const unsigned*)((const char*)(gbase) + (voff)[_i]), (PG8_LAS unsigned*)(lds + (bufoff) + ldsw + _i * 8192), 16, 0, 0); } while (0)
; #define PG8_LDA(dst, b, h) do { _Pragma("unroll") for (int m = 0; m < 4; ++m) _Pragma("unroll") for (int k = 0; k < 2; ++k) dst[m][k] = *(const PG8_LAS bf16x8*)(lds + PG8_SA(b, h) + aoff + m * 2048 + k * 1024); } while (0)
; #define PG8_MMA(ai, bj, At, Bt) do { __builtin_amdgcn_s_setprio(1); _Pragma("unroll") for (int m = 0; m < 4; ++m) _Pragma("unroll") for (int n = 0; n < 2; ++n) _Pragma("unroll") for (int k = 0; k < 2; ++k) \
;         acc[ai][bj][m][n] = __builtin_amdgcn_mfma_f32_16x16x32_bf16(Bt[n][k], At[m][k], acc[ai][bj][m][n], 0, 0, 0); __builtin_amdgcn_s_setprio(0); } while (0)
; #define PG8_WAIT_V(n) asm volatile("s_waitcnt vmcnt(" #n ")" ::: "memory")
; #define PG8_WAIT_L(n) asm volatile("s_waitcnt lgkmcnt(" #n ")" ::: "memory")
; #define PG8_BAR __builtin_amdgcn_s_barrier()
; #define PG8_SCHED __builtin_amdgcn_sched_barrier(0)
; template <class Epi, class Sched, bool ALIGN_EPI = false, bool SP2 = false>
; __device__ __forceinline__ void gemm_phase(PG8_LAS unsigned char* lds, const Gemm g, const Sched& S, const Epi& E) {
;     ...
;             PG8_LDA(At, 1, 1); PG8_STAGE(PG8_SB(1, 0), b3, voffB); PG8_STAGE(PG8_SB(1, 1), b3 + hstep, voffB); PG8_STAGE(PG8_SA(1, 0), a3, voffA);
;             PG8_WAIT_V(8); PG8_WAIT_L(0); PG8_BAR; PG8_MMA(1, 0, At, B0); PG8_MMA(1, 1, At, B1); PG8_BAR; PG8_SCHED;
	s_add_i32 s40, s69, s52
	v_lshl_add_u64 v[150:151], v[150:151], 0, s[10:11]
	s_mov_b32 m0, s40
	ds_read_b128 v[190:193], v156 offset:49152
	ds_read_b128 v[194:197], v156 offset:50176
	ds_read_b128 v[198:201], v156 offset:51200
	ds_read_b128 v[202:205], v156 offset:52224
	ds_read_b128 v[206:209], v156 offset:53248
	ds_read_b128 v[210:213], v156 offset:54272
	ds_read_b128 v[214:217], v156 offset:55296
	ds_read_b128 v[218:221], v156 offset:56320
	global_load_lds_dwordx4 v[150:151], off
	s_add_i32 m0, s40, 0x2000
	s_add_u32 s38, s38, 0x20080
	v_lshl_add_u64 v[150:151], v[170:171], 0, s[10:11]
	s_addc_u32 s39, s39, 0
	s_add_i32 s40, s70, s52
	global_load_lds_dwordx4 v[150:151], off
	v_lshl_add_u64 v[150:151], s[38:39], 0, v[132:133]
	s_mov_b32 m0, s40
	s_nop 0
	global_load_lds_dwordx4 v[150:151], off
	v_lshl_add_u64 v[150:151], s[38:39], 0, v[136:137]
	s_add_i32 m0, s40, 0x2000
	s_nop 0
	global_load_lds_dwordx4 v[150:151], off
	v_lshl_add_u64 v[150:151], v[222:223], 0, s[10:11]
	s_mov_b32 m0, s57
	s_nop 0
	global_load_lds_dwordx4 v[150:151], off
	v_lshl_add_u64 v[150:151], v[224:225], 0, s[10:11]
	s_mov_b32 m0, s58
	s_nop 0
	global_load_lds_dwordx4 v[150:151], off
	s_waitcnt vmcnt(8)
	s_waitcnt lgkmcnt(0)
	s_barrier
	s_setprio 1
	s_waitcnt lgkmcnt(0)
	v_mfma_f32_16x16x32_bf16 v[62:65], v[146:149], v[190:193], v[62:65]
	v_mfma_f32_16x16x32_bf16 v[58:61], v[162:165], v[190:193], v[58:61]
	v_mfma_f32_16x16x32_bf16 v[46:49], v[146:149], v[198:201], v[46:49]
	v_mfma_f32_16x16x32_bf16 v[42:45], v[162:165], v[198:201], v[42:45]
	v_mfma_f32_16x16x32_bf16 v[30:33], v[146:149], v[206:209], v[30:33]
	v_mfma_f32_16x16x32_bf16 v[26:29], v[162:165], v[206:209], v[26:29]
	v_mfma_f32_16x16x32_bf16 v[14:17], v[146:149], v[214:217], v[14:17]
	v_mfma_f32_16x16x32_bf16 v[10:13], v[162:165], v[214:217], v[10:13]
	v_mfma_f32_16x16x32_bf16 v[62:65], v[158:161], v[194:197], v[62:65]
	v_mfma_f32_16x16x32_bf16 v[58:61], v[166:169], v[194:197], v[58:61]
	v_mfma_f32_16x16x32_bf16 v[46:49], v[158:161], v[202:205], v[46:49]
	v_mfma_f32_16x16x32_bf16 v[42:45], v[166:169], v[202:205], v[42:45]
	v_mfma_f32_16x16x32_bf16 v[30:33], v[158:161], v[210:213], v[30:33]
	v_mfma_f32_16x16x32_bf16 v[26:29], v[166:169], v[210:213], v[26:29]
	v_mfma_f32_16x16x32_bf16 v[14:17], v[158:161], v[218:221], v[14:17]
	v_mfma_f32_16x16x32_bf16 v[10:13], v[166:169], v[218:221], v[10:13]
	s_setprio 0
	s_setprio 1
	v_mfma_f32_16x16x32_bf16 v[54:57], v[174:177], v[190:193], v[54:57]
	v_mfma_f32_16x16x32_bf16 v[50:53], v[182:185], v[190:193], v[50:53]
	v_mfma_f32_16x16x32_bf16 v[38:41], v[174:177], v[198:201], v[38:41]
	v_mfma_f32_16x16x32_bf16 v[34:37], v[182:185], v[198:201], v[34:37]
	v_mfma_f32_16x16x32_bf16 v[22:25], v[174:177], v[206:209], v[22:25]
	v_mfma_f32_16x16x32_bf16 v[18:21], v[182:185], v[206:209], v[18:21]
	v_mfma_f32_16x16x32_bf16 v[6:9], v[174:177], v[214:217], v[6:9]
	v_mfma_f32_16x16x32_bf16 v[2:5], v[182:185], v[214:217], v[2:5]
	v_mfma_f32_16x16x32_bf16 v[54:57], v[178:181], v[194:197], v[54:57]
	v_mfma_f32_16x16x32_bf16 v[50:53], v[186:189], v[194:197], v[50:53]
	v_mfma_f32_16x16x32_bf16 v[38:41], v[178:181], v[202:205], v[38:41]
	v_mfma_f32_16x16x32_bf16 v[34:37], v[186:189], v[202:205], v[34:37]
	v_mfma_f32_16x16x32_bf16 v[22:25], v[178:181], v[210:213], v[22:25]
	v_mfma_f32_16x16x32_bf16 v[18:21], v[186:189], v[210:213], v[18:21]
	v_mfma_f32_16x16x32_bf16 v[6:9], v[178:181], v[218:221], v[6:9]
	v_mfma_f32_16x16x32_bf16 v[2:5], v[186:189], v[218:221], v[2:5]
	s_setprio 0
	s_barrier

; template <class Epi, class Sched, bool ALIGN_EPI = false, bool SP2 = false>
; __device__ __forceinline__ void gemm_phase(PG8_LAS unsigned char* lds, const Gemm g, const Sched& S, const Epi& E) {
;     ...
;         for (int t = 0; t < nt; t += 2) {
;             const bool last = (t == nt - 2);
;             const char* a1 = cA + (size_t)(t + 1) * kstep;
;             const char* a2 = last ? nA : cA + (size_t)(t + 2) * kstep; const char* b2 = last ? nB : cB + (size_t)(t + 2) * kstep;
;             const char* a3 = a2 + kstep; const char* b3 = b2 + kstep;
	s_add_i32 s68, s68, 2
	s_add_u32 s34, s34, 0x100
	s_addc_u32 s35, s35, 0
	s_add_u32 s66, s66, 0x100
	s_addc_u32 s67, s67, 0
